# v11 + unrolled PB dot-product loads in P0 + NSA top-k selection loop unrolled x4
# speedup vs baseline: 1.0082x; 1.0082x over previous
; __global__ void __launch_bounds__(512, 2) mega_fwd(Params p) {
;     ...
;         for (int it = gw; it < 256; it += NGW) {
;             const int q = it >> 6, e = it & 63, l = q >> 1, kv = q & 1;
;             const float* pos = (kv ? p.pos_v : p.pos_k) + (size_t)l * 2048; const float* w1 = (kv ? p.w1_v : p.w1_k) + (size_t)l * 2048 * 64;
;             float s = 0.f;
;             for (int f = lane; f < 2048; f += 64) s += pos[f] * w1[(size_t)f * 64 + e];
;             s = wave_sum(s);
;             if (lane == 0) PB[it] = s;
.LBB0_102:
	global_load_dword v104, v[8:9], off
	global_load_dword v136, v[10:11], off
	v_lshl_add_u64 v[8:9], v[8:9], 0, s[2:3]
	v_lshl_add_u64 v[10:11], v[10:11], 0, s[4:5]
	global_load_dword v105, v[8:9], off
	global_load_dword v137, v[10:11], off
	v_lshl_add_u64 v[8:9], v[8:9], 0, s[2:3]
	v_lshl_add_u64 v[10:11], v[10:11], 0, s[4:5]
	global_load_dword v106, v[8:9], off
	global_load_dword v138, v[10:11], off
	v_lshl_add_u64 v[8:9], v[8:9], 0, s[2:3]
	v_lshl_add_u64 v[10:11], v[10:11], 0, s[4:5]
	global_load_dword v107, v[8:9], off
	global_load_dword v139, v[10:11], off
	v_lshl_add_u64 v[8:9], v[8:9], 0, s[2:3]
	v_lshl_add_u64 v[10:11], v[10:11], 0, s[4:5]
	global_load_dword v108, v[8:9], off
	global_load_dword v140, v[10:11], off
	v_lshl_add_u64 v[8:9], v[8:9], 0, s[2:3]
	v_lshl_add_u64 v[10:11], v[10:11], 0, s[4:5]
	global_load_dword v109, v[8:9], off
	global_load_dword v141, v[10:11], off
	v_lshl_add_u64 v[8:9], v[8:9], 0, s[2:3]
	v_lshl_add_u64 v[10:11], v[10:11], 0, s[4:5]
	global_load_dword v110, v[8:9], off
	global_load_dword v142, v[10:11], off
	v_lshl_add_u64 v[8:9], v[8:9], 0, s[2:3]
	v_lshl_add_u64 v[10:11], v[10:11], 0, s[4:5]
	global_load_dword v111, v[8:9], off
	global_load_dword v143, v[10:11], off
	v_lshl_add_u64 v[8:9], v[8:9], 0, s[2:3]
	v_lshl_add_u64 v[10:11], v[10:11], 0, s[4:5]
	global_load_dword v112, v[8:9], off
	global_load_dword v144, v[10:11], off
	v_lshl_add_u64 v[8:9], v[8:9], 0, s[2:3]
	v_lshl_add_u64 v[10:11], v[10:11], 0, s[4:5]
	global_load_dword v113, v[8:9], off
	global_load_dword v145, v[10:11], off
	v_lshl_add_u64 v[8:9], v[8:9], 0, s[2:3]
	v_lshl_add_u64 v[10:11], v[10:11], 0, s[4:5]
	global_load_dword v114, v[8:9], off
	global_load_dword v146, v[10:11], off
	v_lshl_add_u64 v[8:9], v[8:9], 0, s[2:3]
	v_lshl_add_u64 v[10:11], v[10:11], 0, s[4:5]
	global_load_dword v115, v[8:9], off
	global_load_dword v147, v[10:11], off
	v_lshl_add_u64 v[8:9], v[8:9], 0, s[2:3]
	v_lshl_add_u64 v[10:11], v[10:11], 0, s[4:5]
	global_load_dword v116, v[8:9], off
	global_load_dword v148, v[10:11], off
	v_lshl_add_u64 v[8:9], v[8:9], 0, s[2:3]
	v_lshl_add_u64 v[10:11], v[10:11], 0, s[4:5]
	global_load_dword v117, v[8:9], off
	global_load_dword v149, v[10:11], off
	v_lshl_add_u64 v[8:9], v[8:9], 0, s[2:3]
	v_lshl_add_u64 v[10:11], v[10:11], 0, s[4:5]
	global_load_dword v118, v[8:9], off
	global_load_dword v150, v[10:11], off
	v_lshl_add_u64 v[8:9], v[8:9], 0, s[2:3]
	v_lshl_add_u64 v[10:11], v[10:11], 0, s[4:5]
	global_load_dword v119, v[8:9], off
	global_load_dword v151, v[10:11], off
	v_lshl_add_u64 v[8:9], v[8:9], 0, s[2:3]
	v_lshl_add_u64 v[10:11], v[10:11], 0, s[4:5]
	global_load_dword v120, v[8:9], off
	global_load_dword v152, v[10:11], off
	v_lshl_add_u64 v[8:9], v[8:9], 0, s[2:3]
	v_lshl_add_u64 v[10:11], v[10:11], 0, s[4:5]
	global_load_dword v121, v[8:9], off
	global_load_dword v153, v[10:11], off
	v_lshl_add_u64 v[8:9], v[8:9], 0, s[2:3]
	v_lshl_add_u64 v[10:11], v[10:11], 0, s[4:5]
	global_load_dword v122, v[8:9], off
	global_load_dword v154, v[10:11], off
	v_lshl_add_u64 v[8:9], v[8:9], 0, s[2:3]
	v_lshl_add_u64 v[10:11], v[10:11], 0, s[4:5]
	global_load_dword v123, v[8:9], off
	global_load_dword v155, v[10:11], off
	v_lshl_add_u64 v[8:9], v[8:9], 0, s[2:3]
	v_lshl_add_u64 v[10:11], v[10:11], 0, s[4:5]
	global_load_dword v124, v[8:9], off
	global_load_dword v156, v[10:11], off
	v_lshl_add_u64 v[8:9], v[8:9], 0, s[2:3]
	v_lshl_add_u64 v[10:11], v[10:11], 0, s[4:5]
	global_load_dword v125, v[8:9], off
	global_load_dword v157, v[10:11], off
	v_lshl_add_u64 v[8:9], v[8:9], 0, s[2:3]
	v_lshl_add_u64 v[10:11], v[10:11], 0, s[4:5]
	global_load_dword v126, v[8:9], off
	global_load_dword v158, v[10:11], off
	v_lshl_add_u64 v[8:9], v[8:9], 0, s[2:3]
	v_lshl_add_u64 v[10:11], v[10:11], 0, s[4:5]
	global_load_dword v127, v[8:9], off
	global_load_dword v159, v[10:11], off
	v_lshl_add_u64 v[8:9], v[8:9], 0, s[2:3]
	v_lshl_add_u64 v[10:11], v[10:11], 0, s[4:5]
	global_load_dword v128, v[8:9], off
	global_load_dword v160, v[10:11], off
	v_lshl_add_u64 v[8:9], v[8:9], 0, s[2:3]
	v_lshl_add_u64 v[10:11], v[10:11], 0, s[4:5]
	global_load_dword v129, v[8:9], off
	global_load_dword v161, v[10:11], off
	v_lshl_add_u64 v[8:9], v[8:9], 0, s[2:3]
	v_lshl_add_u64 v[10:11], v[10:11], 0, s[4:5]
	global_load_dword v130, v[8:9], off
	global_load_dword v162, v[10:11], off
	v_lshl_add_u64 v[8:9], v[8:9], 0, s[2:3]
	v_lshl_add_u64 v[10:11], v[10:11], 0, s[4:5]
	global_load_dword v131, v[8:9], off
	global_load_dword v163, v[10:11], off
	v_lshl_add_u64 v[8:9], v[8:9], 0, s[2:3]
	v_lshl_add_u64 v[10:11], v[10:11], 0, s[4:5]
	global_load_dword v132, v[8:9], off
	global_load_dword v164, v[10:11], off
	v_lshl_add_u64 v[8:9], v[8:9], 0, s[2:3]
	v_lshl_add_u64 v[10:11], v[10:11], 0, s[4:5]
	global_load_dword v133, v[8:9], off
	global_load_dword v165, v[10:11], off
	v_lshl_add_u64 v[8:9], v[8:9], 0, s[2:3]
	v_lshl_add_u64 v[10:11], v[10:11], 0, s[4:5]
	global_load_dword v134, v[8:9], off
	global_load_dword v166, v[10:11], off
	v_lshl_add_u64 v[8:9], v[8:9], 0, s[2:3]
	v_lshl_add_u64 v[10:11], v[10:11], 0, s[4:5]
	global_load_dword v135, v[8:9], off
	global_load_dword v167, v[10:11], off
	v_lshl_add_u64 v[8:9], v[8:9], 0, s[2:3]
	v_lshl_add_u64 v[10:11], v[10:11], 0, s[4:5]
	s_waitcnt vmcnt(62)
; DI float wave_sum(float v) {
; #pragma unroll
;     for (int o = 1; o < 64; o <<= 1) v += __shfl_xor(v, o);
;     return v;
; }
; __global__ void __launch_bounds__(512, 2) mega_fwd(Params p) {
;     ...
;             for (int f = lane; f < 2048; f += 64) s += pos[f] * w1[(size_t)f * 64 + e];
;             s = wave_sum(s);
;             if (lane == 0) PB[it] = s;
	v_fmac_f32_e32 v18, v104, v136
	s_waitcnt vmcnt(60)
	v_fmac_f32_e32 v18, v105, v137
	s_waitcnt vmcnt(58)
	v_fmac_f32_e32 v18, v106, v138
	s_waitcnt vmcnt(56)
	v_fmac_f32_e32 v18, v107, v139
	s_waitcnt vmcnt(54)
	v_fmac_f32_e32 v18, v108, v140
	s_waitcnt vmcnt(52)
	v_fmac_f32_e32 v18, v109, v141
	s_waitcnt vmcnt(50)
	v_fmac_f32_e32 v18, v110, v142
	s_waitcnt vmcnt(48)
	v_fmac_f32_e32 v18, v111, v143
	s_waitcnt vmcnt(46)
	v_fmac_f32_e32 v18, v112, v144
	s_waitcnt vmcnt(44)
	v_fmac_f32_e32 v18, v113, v145
	s_waitcnt vmcnt(42)
	v_fmac_f32_e32 v18, v114, v146
	s_waitcnt vmcnt(40)
	v_fmac_f32_e32 v18, v115, v147
	s_waitcnt vmcnt(38)
	v_fmac_f32_e32 v18, v116, v148
	s_waitcnt vmcnt(36)
	v_fmac_f32_e32 v18, v117, v149
	s_waitcnt vmcnt(34)
	v_fmac_f32_e32 v18, v118, v150
	s_waitcnt vmcnt(32)
	v_fmac_f32_e32 v18, v119, v151
	s_waitcnt vmcnt(30)
	v_fmac_f32_e32 v18, v120, v152
	s_waitcnt vmcnt(28)
	v_fmac_f32_e32 v18, v121, v153
	s_waitcnt vmcnt(26)
	v_fmac_f32_e32 v18, v122, v154
	s_waitcnt vmcnt(24)
	v_fmac_f32_e32 v18, v123, v155
	s_waitcnt vmcnt(22)
	v_fmac_f32_e32 v18, v124, v156
	s_waitcnt vmcnt(20)
	v_fmac_f32_e32 v18, v125, v157
	s_waitcnt vmcnt(18)
	v_fmac_f32_e32 v18, v126, v158
	s_waitcnt vmcnt(16)
	v_fmac_f32_e32 v18, v127, v159
	s_waitcnt vmcnt(14)
	v_fmac_f32_e32 v18, v128, v160
	s_waitcnt vmcnt(12)
	v_fmac_f32_e32 v18, v129, v161
	s_waitcnt vmcnt(10)
	v_fmac_f32_e32 v18, v130, v162
	s_waitcnt vmcnt(8)
	v_fmac_f32_e32 v18, v131, v163
	s_waitcnt vmcnt(6)
	v_fmac_f32_e32 v18, v132, v164
	s_waitcnt vmcnt(4)
	v_fmac_f32_e32 v18, v133, v165
	s_waitcnt vmcnt(2)
	v_fmac_f32_e32 v18, v134, v166
	s_waitcnt vmcnt(0)
	v_fmac_f32_e32 v18, v135, v167
	s_or_b64 exec, exec, s[18:19]
	ds_bpermute_b32 v8, v3, v18
	s_waitcnt lgkmcnt(0)
	v_add_f32_e32 v8, v18, v8
	ds_bpermute_b32 v9, v12, v8
	s_waitcnt lgkmcnt(0)
	v_add_f32_e32 v8, v8, v9
	ds_bpermute_b32 v9, v13, v8
	s_waitcnt lgkmcnt(0)
	v_add_f32_e32 v8, v8, v9
	ds_bpermute_b32 v9, v14, v8
	s_waitcnt lgkmcnt(0)
	v_add_f32_e32 v8, v8, v9
	ds_bpermute_b32 v9, v15, v8
	s_waitcnt lgkmcnt(0)
	v_add_f32_e32 v8, v8, v9
	ds_bpermute_b32 v9, v16, v8
	s_and_saveexec_b64 s[0:1], vcc
	s_cbranch_execz .LBB0_100
	s_ashr_i32 s7, s6, 31
	s_lshl_b64 s[18:19], s[6:7], 2
	v_readlane_b32 s7, v245, 31
	s_add_u32 s18, s7, s18
	v_readlane_b32 s7, v245, 32
	s_addc_u32 s19, s7, s19
	s_waitcnt lgkmcnt(0)
	v_add_f32_e32 v8, v8, v9
	global_store_dword v5, v8, s[18:19]
	s_branch .LBB0_100

; DI void nsa_unit(const bf16* PR, const float* AUX, const bf16* KC, const bf16* VC, bf16* MIX, char* sm, int b, int qb) {
;     ...
;                 for (int r = 0; r < nfree; ++r) { float best = -1.f; int bj = 1;
;                     for (int j = 1; j <= cur - 2; ++j) { const float v = rowp[j]; if (v > best) { best = v; bj = j; } }
;                     selbits |= 1u << bj; rowp[bj] = -2.f; }
.Lsel4_head:
	s_sub_i32 s6, s1, s5
	s_cmp_lt_i32 s6, 4
	s_cbranch_scc1 .Lsel_tail
	ds_read2_b32 v[246:247], v6 offset1:1
	ds_read2_b32 v[248:249], v6 offset0:2 offset1:3
	s_add_i32 s6, s5, 30
	v_mov_b32_e32 v250, s6
	v_add_u32_e32 v251, 1, v250
	v_add_u32_e32 v253, 2, v250
	v_add_u32_e32 v254, 3, v250
	s_add_i32 s5, s5, 4
	v_add_u32_e32 v6, 16, v6
	s_waitcnt lgkmcnt(1)
	v_cmp_gt_f32_e32 vcc, v246, v5
	s_nop 1
	v_cndmask_b32_e32 v4, v4, v250, vcc
	v_cndmask_b32_e32 v5, v5, v246, vcc
	v_cmp_gt_f32_e32 vcc, v247, v5
	s_nop 1
	v_cndmask_b32_e32 v4, v4, v251, vcc
	v_cndmask_b32_e32 v5, v5, v247, vcc
	s_waitcnt lgkmcnt(0)
	v_cmp_gt_f32_e32 vcc, v248, v5
	s_nop 1
	v_cndmask_b32_e32 v4, v4, v253, vcc
	v_cndmask_b32_e32 v5, v5, v248, vcc
	v_cmp_gt_f32_e32 vcc, v249, v5
	s_nop 1
	v_cndmask_b32_e32 v4, v4, v254, vcc
	v_cndmask_b32_e32 v5, v5, v249, vcc
	s_branch .Lsel4_head
.Lsel_tail:
	s_cmp_eq_u32 s6, 0
	s_cbranch_scc1 .Lsel_done

; DI void nsa_unit(const bf16* PR, const float* AUX, const bf16* KC, const bf16* VC, bf16* MIX, char* sm, int b, int qb) {
;     ...
;                 for (int r = 0; r < nfree; ++r) { float best = -1.f; int bj = 1;
;                     for (int j = 1; j <= cur - 2; ++j) { const float v = rowp[j]; if (v > best) { best = v; bj = j; } }
;                     selbits |= 1u << bj; rowp[bj] = -2.f; }
.Lsel_done:
	s_add_i32 s0, s0, 1
	v_lshl_or_b32 v2, 1, v4, v2
	v_lshl_add_u32 v4, v4, 2, v3
	s_cmp_ge_i32 s0, s4
	ds_write_b32 v4, v177 offset:45056
	s_cbranch_scc0 .LBB0_505
